# ffn-up epilogue stores: sc1 (agent-scope write-through) instead of sc0 sc1
# speedup vs baseline: 1.0036x; 1.0036x over previous
; #define LAS __attribute__((address_space(3)))
; __device__ __forceinline__ unsigned cvtpk(float lo, float hi) { f32x2 v = {lo, hi}; bf16x2_t b = __builtin_convertvector(v, bf16x2_t); return __builtin_bit_cast(unsigned, b); }
;     __device__ __forceinline__ void operator()(const f32x4 (&acc)[2][2][4][2], const Unit& u, int wr, int wc, int fr, int fq, const LAS float* tab) const {
;     ...
;             if (MODE != 0) {
; #pragma unroll
;                 for (int i = 0; i < 8; ++i) rs[i] = tab[wr * 64 + fr_ + (i >> 2) * HALF + (i & 3) * 16]; }
; #pragma unroll
;             for (int bj = 0; bj < 2; ++bj) {
;                 f32x4 b0 = {0.f, 0.f, 0.f, 0.f}, b1 = b0;
;                 if (MODE != 0) { const LAS float* bp = tab + 256 + wc * 32 + 8 * fq_ + bj * HALF; b0 = *(const LAS f32x4*)bp; b1 = *(const LAS f32x4*)(bp + 4); }
; #pragma unroll
;                 for (int i = 0; i < 8; ++i) { const int ai = i >> 2, m = i & 3; bf16_t* rowp = base + (size_t)(row0 + ai * HALF + m * 16) * ld + c0;
;                     if (MODE == 1 && (u.pn == 4 || u.pn == 5)) {
;                         const bool isx = u.pm < MX / BM; const int bb = isx ? (u.pm >> 3) : (u.pm - MX / BM), ar0 = isx ? CTX + (u.pm & 7) * BM : 0;
;                         rowp = Hout + ((size_t)(bb * 4 + 2 * (u.pn - 4) + bj) * TK + ar0 + wr * 64 + fr_ + ai * HALF + m * 16) * 128 + wc * 32 + 8 * fq_ - bj * HALF; }
;                     f32x4 v0 = acc[ai][bj][m][0], v1 = acc[ai][bj][m][1];
;                     if (MODE != 0) { v0 = v0 * rs[i] + b0; v1 = v1 * rs[i] + b1; }
;                     if (MODE == 4) {
; #pragma unroll
;                         for (int e = 0; e < 4; ++e) { float a = fmaxf(v0[e], 0.f), b = fmaxf(v1[e], 0.f); v0[e] = a * a; v1[e] = b * b; } }
;                     u32x4 w; w.x = cvtpk(v0[0], v0[1]); w.y = cvtpk(v0[2], v0[3]); w.z = cvtpk(v1[0], v1[1]); w.w = cvtpk(v1[2], v1[3]);
;                     *(u32x4*)(rowp + bj * HALF) = w; } }
.LBB0_1274:
	s_lshl_b32 s13, s20, 8
	v_mbcnt_lo_u32_b32 v128, -1, 0
	v_mbcnt_hi_u32_b32 v128, -1, v128
	s_add_i32 s13, s13, s47
	v_and_b32_e32 v129, 15, v128
	s_lshl_b32 s11, s50, 11
	v_or_b32_e32 v156, s13, v129
	v_ashrrev_i32_e32 v128, 1, v128
	s_lshl_b32 s13, s18, 8
	s_add_i32 s11, s11, 0
	v_and_b32_e32 v128, -8, v128
	s_or_b32 s13, s13, s48
	s_add_i32 s11, s11, 0x20400
	s_lshl_b32 s18, s47, 2
	v_add_u32_e32 v154, s13, v128
	s_lshl_b32 s13, s48, 2
	s_add_i32 s18, s11, s18
	s_add_i32 s11, s11, s13
	v_lshl_add_u32 v129, v129, 2, s18
	v_lshl_add_u32 v162, v128, 2, s11
	ds_read2_b32 v[152:153], v129 offset1:16
	ds_read2_b32 v[150:151], v129 offset0:32 offset1:48
	ds_read2_b32 v[148:149], v129 offset0:128 offset1:144
	ds_read2_b32 v[146:147], v129 offset0:160 offset1:176
	ds_read_b128 v[132:135], v162 offset:1024
	ds_read_b128 v[128:131], v162 offset:1040
	v_ashrrev_i32_e32 v155, 31, v154
	v_ashrrev_i32_e32 v157, 31, v156
	v_lshl_add_u64 v[154:155], v[154:155], 1, s[6:7]
	s_waitcnt lgkmcnt(0)
	v_pk_fma_f32 v[124:125], v[124:125], v[152:153], v[132:133] op_sel_hi:[1,0,1]
	v_pk_fma_f32 v[120:121], v[120:121], v[152:153], v[128:129] op_sel_hi:[1,0,1]
	v_pk_fma_f32 v[126:127], v[126:127], v[152:153], v[134:135] op_sel_hi:[1,0,1]
	v_pk_fma_f32 v[122:123], v[122:123], v[152:153], v[130:131] op_sel_hi:[1,0,1]
	v_max_f32_e32 v124, 0, v124
	v_max_f32_e32 v120, 0, v120
	v_max_f32_e32 v125, 0, v125
	v_max_f32_e32 v121, 0, v121
	v_pk_mul_f32 v[124:125], v[124:125], v[124:125]
	v_pk_mul_f32 v[120:121], v[120:121], v[120:121]
	v_max_f32_e32 v126, 0, v126
	v_max_f32_e32 v122, 0, v122
	v_max_f32_e32 v127, 0, v127
	v_max_f32_e32 v123, 0, v123
	v_pk_mul_f32 v[126:127], v[126:127], v[126:127]
	v_pk_mul_f32 v[160:161], v[122:123], v[122:123]
	v_cvt_pk_bf16_f32 v122, v124, v125
	v_cvt_pk_bf16_f32 v124, v120, v121
	v_lshlrev_b64 v[120:121], 13, v[156:157]
	v_cvt_pk_bf16_f32 v123, v126, v127
	v_cvt_pk_bf16_f32 v125, v160, v161
	v_lshl_add_u64 v[120:121], v[154:155], 0, v[120:121]
	global_store_dwordx4 v[120:121], v[122:125], off sc1
	v_pk_fma_f32 v[108:109], v[108:109], v[150:151], v[132:133] op_sel_hi:[1,0,1]
	v_pk_fma_f32 v[104:105], v[104:105], v[150:151], v[128:129] op_sel_hi:[1,0,1]
	v_mov_b32_e32 v122, v153
	v_pk_fma_f32 v[116:117], v[116:117], v[122:123], v[132:133] op_sel_hi:[1,0,1]
	v_pk_fma_f32 v[112:113], v[112:113], v[122:123], v[128:129] op_sel_hi:[1,0,1]
	v_or_b32_e32 v124, 16, v156
	v_pk_fma_f32 v[118:119], v[118:119], v[122:123], v[134:135] op_sel_hi:[1,0,1]
	v_pk_fma_f32 v[114:115], v[114:115], v[122:123], v[130:131] op_sel_hi:[1,0,1]
	v_max_f32_e32 v116, 0, v116
	v_max_f32_e32 v112, 0, v112
	v_max_f32_e32 v117, 0, v117
	v_max_f32_e32 v113, 0, v113
	v_ashrrev_i32_e32 v125, 31, v124
	v_pk_mul_f32 v[116:117], v[116:117], v[116:117]
	v_pk_mul_f32 v[112:113], v[112:113], v[112:113]
	v_max_f32_e32 v118, 0, v118
	v_max_f32_e32 v114, 0, v114
	v_max_f32_e32 v119, 0, v119
	v_max_f32_e32 v115, 0, v115
	v_pk_mul_f32 v[118:119], v[118:119], v[118:119]
	v_pk_mul_f32 v[126:127], v[114:115], v[114:115]
	v_cvt_pk_bf16_f32 v114, v116, v117
	v_cvt_pk_bf16_f32 v116, v112, v113
	v_lshlrev_b64 v[112:113], 13, v[124:125]
	v_cvt_pk_bf16_f32 v115, v118, v119
	v_cvt_pk_bf16_f32 v117, v126, v127
	v_lshl_add_u64 v[112:113], v[154:155], 0, v[112:113]
	global_store_dwordx4 v[112:113], v[114:117], off sc1
	v_pk_fma_f32 v[110:111], v[110:111], v[150:151], v[134:135] op_sel_hi:[1,0,1]
	v_pk_fma_f32 v[106:107], v[106:107], v[150:151], v[130:131] op_sel_hi:[1,0,1]
	v_or_b32_e32 v114, 32, v156
	v_max_f32_e32 v108, 0, v108
	v_max_f32_e32 v104, 0, v104
	v_max_f32_e32 v109, 0, v109
	v_max_f32_e32 v105, 0, v105
	v_ashrrev_i32_e32 v115, 31, v114
	v_pk_mul_f32 v[108:109], v[108:109], v[108:109]
	v_pk_mul_f32 v[104:105], v[104:105], v[104:105]
	v_max_f32_e32 v110, 0, v110
	v_max_f32_e32 v106, 0, v106
	v_max_f32_e32 v111, 0, v111
	v_max_f32_e32 v107, 0, v107
	v_pk_mul_f32 v[110:111], v[110:111], v[110:111]
	v_pk_mul_f32 v[116:117], v[106:107], v[106:107]
	v_cvt_pk_bf16_f32 v106, v108, v109
	v_cvt_pk_bf16_f32 v108, v104, v105
	v_lshlrev_b64 v[104:105], 13, v[114:115]
	v_cvt_pk_bf16_f32 v107, v110, v111
	v_cvt_pk_bf16_f32 v109, v116, v117
	v_lshl_add_u64 v[104:105], v[154:155], 0, v[104:105]
	global_store_dwordx4 v[104:105], v[106:109], off sc1
	v_pk_fma_f32 v[94:95], v[94:95], v[148:149], v[134:135] op_sel_hi:[1,0,1]
	v_pk_fma_f32 v[92:93], v[92:93], v[148:149], v[132:133] op_sel_hi:[1,0,1]
	v_mov_b32_e32 v106, v151
	v_pk_fma_f32 v[100:101], v[100:101], v[106:107], v[132:133] op_sel_hi:[1,0,1]
	v_pk_fma_f32 v[96:97], v[96:97], v[106:107], v[128:129] op_sel_hi:[1,0,1]
	v_or_b32_e32 v108, 48, v156
	v_pk_fma_f32 v[102:103], v[102:103], v[106:107], v[134:135] op_sel_hi:[1,0,1]
	v_pk_fma_f32 v[98:99], v[98:99], v[106:107], v[130:131] op_sel_hi:[1,0,1]
	v_max_f32_e32 v100, 0, v100
	v_max_f32_e32 v96, 0, v96
	v_max_f32_e32 v101, 0, v101
	v_max_f32_e32 v97, 0, v97
	v_ashrrev_i32_e32 v109, 31, v108
	v_pk_mul_f32 v[100:101], v[100:101], v[100:101]
	v_pk_mul_f32 v[96:97], v[96:97], v[96:97]
	v_max_f32_e32 v102, 0, v102
	v_max_f32_e32 v98, 0, v98
	v_max_f32_e32 v103, 0, v103
	v_max_f32_e32 v99, 0, v99
	v_pk_mul_f32 v[102:103], v[102:103], v[102:103]
	v_pk_mul_f32 v[110:111], v[98:99], v[98:99]
	v_cvt_pk_bf16_f32 v98, v100, v101
	v_cvt_pk_bf16_f32 v100, v96, v97
	v_lshlrev_b64 v[96:97], 13, v[108:109]
	v_pk_fma_f32 v[90:91], v[90:91], v[148:149], v[130:131] op_sel_hi:[1,0,1]
	v_pk_fma_f32 v[88:89], v[88:89], v[148:149], v[128:129] op_sel_hi:[1,0,1]
	v_max_f32_e32 v94, 0, v94
	v_max_f32_e32 v95, 0, v95
	v_cvt_pk_bf16_f32 v99, v102, v103
	v_cvt_pk_bf16_f32 v101, v110, v111
	v_lshl_add_u64 v[96:97], v[154:155], 0, v[96:97]
; __device__ __forceinline__ unsigned cvtpk(float lo, float hi) { f32x2 v = {lo, hi}; bf16x2_t b = __builtin_convertvector(v, bf16x2_t); return __builtin_bit_cast(unsigned, b); }
;     __device__ __forceinline__ void operator()(const f32x4 (&acc)[2][2][4][2], const Unit& u, int wr, int wc, int fr, int fq, const LAS float* tab) const {
;     ...
;                 for (int i = 0; i < 8; ++i) { const int ai = i >> 2, m = i & 3; bf16_t* rowp = base + (size_t)(row0 + ai * HALF + m * 16) * ld + c0;
;                     if (MODE == 1 && (u.pn == 4 || u.pn == 5)) {
;                         const bool isx = u.pm < MX / BM; const int bb = isx ? (u.pm >> 3) : (u.pm - MX / BM), ar0 = isx ? CTX + (u.pm & 7) * BM : 0;
;                         rowp = Hout + ((size_t)(bb * 4 + 2 * (u.pn - 4) + bj) * TK + ar0 + wr * 64 + fr_ + ai * HALF + m * 16) * 128 + wc * 32 + 8 * fq_ - bj * HALF; }
;                     f32x4 v0 = acc[ai][bj][m][0], v1 = acc[ai][bj][m][1];
;                     if (MODE != 0) { v0 = v0 * rs[i] + b0; v1 = v1 * rs[i] + b1; }
;                     if (MODE == 4) {
; #pragma unroll
;                         for (int e = 0; e < 4; ++e) { float a = fmaxf(v0[e], 0.f), b = fmaxf(v1[e], 0.f); v0[e] = a * a; v1[e] = b * b; } }
;                     u32x4 w; w.x = cvtpk(v0[0], v0[1]); w.y = cvtpk(v0[2], v0[3]); w.z = cvtpk(v1[0], v1[1]); w.w = cvtpk(v1[2], v1[3]);
;                     *(u32x4*)(rowp + bj * HALF) = w; } }
	v_max_f32_e32 v92, 0, v92
	v_max_f32_e32 v88, 0, v88
	v_max_f32_e32 v93, 0, v93
	v_max_f32_e32 v89, 0, v89
	v_max_f32_e32 v90, 0, v90
	v_max_f32_e32 v91, 0, v91
	v_pk_mul_f32 v[94:95], v[94:95], v[94:95]
	s_mov_b32 s11, 0x100000
	global_store_dwordx4 v[96:97], v[98:101], off sc1
	v_pk_mul_f32 v[92:93], v[92:93], v[92:93]
	v_pk_mul_f32 v[88:89], v[88:89], v[88:89]
	v_pk_mul_f32 v[98:99], v[90:91], v[90:91]
	v_cvt_pk_bf16_f32 v91, v94, v95
	v_add_co_u32_e32 v94, vcc, s11, v120
	v_cvt_pk_bf16_f32 v90, v92, v93
	v_cvt_pk_bf16_f32 v92, v88, v89
	v_cvt_pk_bf16_f32 v93, v98, v99
	v_addc_co_u32_e32 v95, vcc, 0, v121, vcc
	global_store_dwordx4 v[94:95], v[90:93], off sc1
	v_pk_fma_f32 v[76:77], v[76:77], v[146:147], v[132:133] op_sel_hi:[1,0,1]
	v_pk_fma_f32 v[72:73], v[72:73], v[146:147], v[128:129] op_sel_hi:[1,0,1]
	v_mov_b32_e32 v90, v149
	v_pk_fma_f32 v[84:85], v[84:85], v[90:91], v[132:133] op_sel_hi:[1,0,1]
	v_pk_fma_f32 v[80:81], v[80:81], v[90:91], v[128:129] op_sel_hi:[1,0,1]
	v_add_u32_e32 v92, 0x90, v156
	v_pk_fma_f32 v[86:87], v[86:87], v[90:91], v[134:135] op_sel_hi:[1,0,1]
	v_pk_fma_f32 v[82:83], v[82:83], v[90:91], v[130:131] op_sel_hi:[1,0,1]
	v_max_f32_e32 v84, 0, v84
	v_max_f32_e32 v80, 0, v80
	v_max_f32_e32 v85, 0, v85
	v_max_f32_e32 v81, 0, v81
	v_ashrrev_i32_e32 v93, 31, v92
	v_pk_mul_f32 v[84:85], v[84:85], v[84:85]
	v_pk_mul_f32 v[80:81], v[80:81], v[80:81]
	v_max_f32_e32 v86, 0, v86
	v_max_f32_e32 v82, 0, v82
	v_max_f32_e32 v87, 0, v87
	v_max_f32_e32 v83, 0, v83
	v_pk_mul_f32 v[86:87], v[86:87], v[86:87]
	v_pk_mul_f32 v[94:95], v[82:83], v[82:83]
	v_cvt_pk_bf16_f32 v82, v84, v85
	v_cvt_pk_bf16_f32 v84, v80, v81
	v_lshlrev_b64 v[80:81], 13, v[92:93]
	v_cvt_pk_bf16_f32 v83, v86, v87
	v_cvt_pk_bf16_f32 v85, v94, v95
	v_lshl_add_u64 v[80:81], v[154:155], 0, v[80:81]
	global_store_dwordx4 v[80:81], v[82:85], off sc1
	v_pk_fma_f32 v[78:79], v[78:79], v[146:147], v[134:135] op_sel_hi:[1,0,1]
	v_pk_fma_f32 v[74:75], v[74:75], v[146:147], v[130:131] op_sel_hi:[1,0,1]
	v_add_u32_e32 v82, 0xa0, v156
	v_max_f32_e32 v76, 0, v76
	v_max_f32_e32 v72, 0, v72
	v_max_f32_e32 v77, 0, v77
	v_max_f32_e32 v73, 0, v73
	v_ashrrev_i32_e32 v83, 31, v82
	v_pk_mul_f32 v[76:77], v[76:77], v[76:77]
	v_pk_mul_f32 v[72:73], v[72:73], v[72:73]
	v_max_f32_e32 v78, 0, v78
	v_max_f32_e32 v74, 0, v74
	v_max_f32_e32 v79, 0, v79
	v_max_f32_e32 v75, 0, v75
	v_pk_mul_f32 v[78:79], v[78:79], v[78:79]
	v_pk_mul_f32 v[84:85], v[74:75], v[74:75]
	v_cvt_pk_bf16_f32 v74, v76, v77
	v_cvt_pk_bf16_f32 v76, v72, v73
	v_lshlrev_b64 v[72:73], 13, v[82:83]
	v_cvt_pk_bf16_f32 v75, v78, v79
	v_cvt_pk_bf16_f32 v77, v84, v85
	v_lshl_add_u64 v[72:73], v[154:155], 0, v[72:73]
	global_store_dwordx4 v[72:73], v[74:77], off sc1
	s_mov_b64 s[22:23], 0x100000
	v_lshl_add_u64 v[88:89], v[120:121], 0, s[22:23]
	v_mov_b32_e32 v74, v147
	v_pk_fma_f32 v[62:63], v[62:63], v[74:75], v[134:135] op_sel_hi:[1,0,1]
	v_pk_fma_f32 v[60:61], v[60:61], v[74:75], v[132:133] op_sel_hi:[1,0,1]
	v_pk_fma_f32 v[58:59], v[58:59], v[74:75], v[130:131] op_sel_hi:[1,0,1]
	v_pk_fma_f32 v[56:57], v[56:57], v[74:75], v[128:129] op_sel_hi:[1,0,1]
	v_max_f32_e32 v60, 0, v60
	v_max_f32_e32 v56, 0, v56
	v_max_f32_e32 v61, 0, v61
	v_max_f32_e32 v57, 0, v57
	v_max_f32_e32 v62, 0, v62
	v_max_f32_e32 v58, 0, v58
	v_max_f32_e32 v63, 0, v63
	v_max_f32_e32 v59, 0, v59
	v_pk_mul_f32 v[60:61], v[60:61], v[60:61]
	v_pk_mul_f32 v[56:57], v[56:57], v[56:57]
	v_pk_mul_f32 v[62:63], v[62:63], v[62:63]
	v_pk_mul_f32 v[58:59], v[58:59], v[58:59]
	v_cvt_pk_bf16_f32 v82, v60, v61
	v_cvt_pk_bf16_f32 v83, v62, v63
	v_cvt_pk_bf16_f32 v84, v56, v57
	v_cvt_pk_bf16_f32 v85, v58, v59
	ds_read_b128 v[60:63], v162 offset:1536
	ds_read_b128 v[56:59], v162 offset:1552
	v_add_u32_e32 v76, 0xb0, v156
	v_ashrrev_i32_e32 v77, 31, v76
	v_lshlrev_b64 v[76:77], 13, v[76:77]
	s_waitcnt lgkmcnt(0)
	v_pk_fma_f32 v[70:71], v[70:71], v[152:153], v[62:63] op_sel_hi:[1,0,1]
	v_pk_fma_f32 v[64:65], v[64:65], v[152:153], v[56:57] op_sel_hi:[1,0,1]
	v_pk_fma_f32 v[68:69], v[68:69], v[152:153], v[60:61] op_sel_hi:[1,0,1]
	v_pk_fma_f32 v[66:67], v[66:67], v[152:153], v[58:59] op_sel_hi:[1,0,1]
	v_max_f32_e32 v64, 0, v64
	v_max_f32_e32 v65, 0, v65
	v_lshl_add_u64 v[76:77], v[154:155], 0, v[76:77]
	v_max_f32_e32 v68, 0, v68
	v_max_f32_e32 v69, 0, v69
	v_pk_mul_f32 v[78:79], v[64:65], v[64:65]
	v_max_f32_e32 v64, 0, v70
	v_max_f32_e32 v66, 0, v66
	v_max_f32_e32 v65, 0, v71
	v_max_f32_e32 v67, 0, v67
	global_store_dwordx4 v[76:77], v[82:85], off sc1
	v_pk_mul_f32 v[68:69], v[68:69], v[68:69]
	v_pk_mul_f32 v[70:71], v[64:65], v[64:65]
	v_pk_mul_f32 v[82:83], v[66:67], v[66:67]
	v_pk_fma_f32 v[48:49], v[48:49], v[122:123], v[56:57] op_sel_hi:[1,0,1]
	v_cvt_pk_bf16_f32 v64, v68, v69
	v_cvt_pk_bf16_f32 v65, v70, v71
	v_cvt_pk_bf16_f32 v66, v78, v79
	v_cvt_pk_bf16_f32 v67, v82, v83
	v_pk_fma_f32 v[54:55], v[54:55], v[122:123], v[62:63] op_sel_hi:[1,0,1]
	v_pk_fma_f32 v[52:53], v[52:53], v[122:123], v[60:61] op_sel_hi:[1,0,1]
	v_pk_fma_f32 v[50:51], v[50:51], v[122:123], v[58:59] op_sel_hi:[1,0,1]
	v_max_f32_e32 v48, 0, v48
	v_max_f32_e32 v49, 0, v49
	global_store_dwordx4 v[120:121], v[64:67], off offset:256 sc1
	v_max_f32_e32 v52, 0, v52
	v_max_f32_e32 v53, 0, v53
	v_pk_mul_f32 v[64:65], v[48:49], v[48:49]
	v_max_f32_e32 v48, 0, v54
	v_max_f32_e32 v50, 0, v50
	v_max_f32_e32 v49, 0, v55
	v_max_f32_e32 v51, 0, v51
	v_pk_mul_f32 v[52:53], v[52:53], v[52:53]
	v_pk_mul_f32 v[54:55], v[48:49], v[48:49]
	v_pk_mul_f32 v[66:67], v[50:51], v[50:51]
	v_pk_fma_f32 v[40:41], v[40:41], v[150:151], v[56:57] op_sel_hi:[1,0,1]
	v_cvt_pk_bf16_f32 v48, v52, v53
; __device__ __forceinline__ unsigned cvtpk(float lo, float hi) { f32x2 v = {lo, hi}; bf16x2_t b = __builtin_convertvector(v, bf16x2_t); return __builtin_bit_cast(unsigned, b); }
; #define PG8_BAR __builtin_amdgcn_s_barrier()
;     __device__ __forceinline__ void operator()(const f32x4 (&acc)[2][2][4][2], const Unit& u, int wr, int wc, int fr, int fq, const LAS float* tab) const {
;     ...
;                 for (int i = 0; i < 8; ++i) { const int ai = i >> 2, m = i & 3; bf16_t* rowp = base + (size_t)(row0 + ai * HALF + m * 16) * ld + c0;
;                     if (MODE == 1 && (u.pn == 4 || u.pn == 5)) {
;                         const bool isx = u.pm < MX / BM; const int bb = isx ? (u.pm >> 3) : (u.pm - MX / BM), ar0 = isx ? CTX + (u.pm & 7) * BM : 0;
;                         rowp = Hout + ((size_t)(bb * 4 + 2 * (u.pn - 4) + bj) * TK + ar0 + wr * 64 + fr_ + ai * HALF + m * 16) * 128 + wc * 32 + 8 * fq_ - bj * HALF; }
;                     f32x4 v0 = acc[ai][bj][m][0], v1 = acc[ai][bj][m][1];
;                     if (MODE != 0) { v0 = v0 * rs[i] + b0; v1 = v1 * rs[i] + b1; }
;                     if (MODE == 4) {
; #pragma unroll
;                         for (int e = 0; e < 4; ++e) { float a = fmaxf(v0[e], 0.f), b = fmaxf(v1[e], 0.f); v0[e] = a * a; v1[e] = b * b; } }
;                     u32x4 w; w.x = cvtpk(v0[0], v0[1]); w.y = cvtpk(v0[2], v0[3]); w.z = cvtpk(v1[0], v1[1]); w.w = cvtpk(v1[2], v1[3]);
;                     *(u32x4*)(rowp + bj * HALF) = w; } }
; template <class EpiT, class Sched>
; __device__ __forceinline__ void gemm_phase(LAS unsigned char* lds, const Gemm g, const Sched& S, const EpiT& E, int wv) {
;     ...
;         if (wr == 0) PG8_BAR;
;         E(acc, cur, wr, wc, fr, fq, EpiT::TAB ? tab + ui * 512 : tab);
	v_cvt_pk_bf16_f32 v49, v54, v55
	v_cvt_pk_bf16_f32 v50, v64, v65
	v_cvt_pk_bf16_f32 v51, v66, v67
	v_pk_fma_f32 v[46:47], v[46:47], v[150:151], v[62:63] op_sel_hi:[1,0,1]
	v_pk_fma_f32 v[44:45], v[44:45], v[150:151], v[60:61] op_sel_hi:[1,0,1]
	v_pk_fma_f32 v[42:43], v[42:43], v[150:151], v[58:59] op_sel_hi:[1,0,1]
	v_max_f32_e32 v40, 0, v40
	v_max_f32_e32 v41, 0, v41
	global_store_dwordx4 v[112:113], v[48:51], off offset:256 sc1
	v_max_f32_e32 v44, 0, v44
	v_max_f32_e32 v45, 0, v45
	v_pk_mul_f32 v[48:49], v[40:41], v[40:41]
	v_max_f32_e32 v40, 0, v46
	v_max_f32_e32 v42, 0, v42
	v_max_f32_e32 v41, 0, v47
	v_max_f32_e32 v43, 0, v43
	v_pk_mul_f32 v[44:45], v[44:45], v[44:45]
	v_pk_mul_f32 v[46:47], v[40:41], v[40:41]
	v_pk_mul_f32 v[50:51], v[42:43], v[42:43]
	v_pk_fma_f32 v[32:33], v[32:33], v[106:107], v[56:57] op_sel_hi:[1,0,1]
	v_cvt_pk_bf16_f32 v40, v44, v45
	v_cvt_pk_bf16_f32 v41, v46, v47
	v_cvt_pk_bf16_f32 v42, v48, v49
	v_cvt_pk_bf16_f32 v43, v50, v51
	v_pk_fma_f32 v[38:39], v[38:39], v[106:107], v[62:63] op_sel_hi:[1,0,1]
	v_pk_fma_f32 v[36:37], v[36:37], v[106:107], v[60:61] op_sel_hi:[1,0,1]
	v_pk_fma_f32 v[34:35], v[34:35], v[106:107], v[58:59] op_sel_hi:[1,0,1]
	v_max_f32_e32 v32, 0, v32
	v_max_f32_e32 v33, 0, v33
	global_store_dwordx4 v[104:105], v[40:43], off offset:256 sc1
	v_max_f32_e32 v36, 0, v36
	v_max_f32_e32 v37, 0, v37
	v_pk_mul_f32 v[40:41], v[32:33], v[32:33]
	v_max_f32_e32 v32, 0, v38
	v_max_f32_e32 v34, 0, v34
	v_max_f32_e32 v33, 0, v39
	v_max_f32_e32 v35, 0, v35
	v_pk_mul_f32 v[36:37], v[36:37], v[36:37]
	v_pk_mul_f32 v[38:39], v[32:33], v[32:33]
	v_pk_mul_f32 v[42:43], v[34:35], v[34:35]
	v_pk_fma_f32 v[24:25], v[24:25], v[148:149], v[56:57] op_sel_hi:[1,0,1]
	v_cvt_pk_bf16_f32 v32, v36, v37
	v_cvt_pk_bf16_f32 v33, v38, v39
	v_cvt_pk_bf16_f32 v34, v40, v41
	v_cvt_pk_bf16_f32 v35, v42, v43
	v_pk_fma_f32 v[30:31], v[30:31], v[148:149], v[62:63] op_sel_hi:[1,0,1]
	v_pk_fma_f32 v[28:29], v[28:29], v[148:149], v[60:61] op_sel_hi:[1,0,1]
	v_pk_fma_f32 v[26:27], v[26:27], v[148:149], v[58:59] op_sel_hi:[1,0,1]
	v_max_f32_e32 v24, 0, v24
	v_max_f32_e32 v25, 0, v25
	global_store_dwordx4 v[96:97], v[32:35], off offset:256 sc1
	v_max_f32_e32 v28, 0, v28
	v_max_f32_e32 v29, 0, v29
	v_pk_mul_f32 v[32:33], v[24:25], v[24:25]
	v_max_f32_e32 v24, 0, v30
	v_max_f32_e32 v26, 0, v26
	v_max_f32_e32 v25, 0, v31
	v_max_f32_e32 v27, 0, v27
	v_pk_mul_f32 v[28:29], v[28:29], v[28:29]
	v_pk_mul_f32 v[30:31], v[24:25], v[24:25]
	v_pk_mul_f32 v[34:35], v[26:27], v[26:27]
	v_pk_fma_f32 v[16:17], v[16:17], v[90:91], v[56:57] op_sel_hi:[1,0,1]
	v_cvt_pk_bf16_f32 v24, v28, v29
	v_cvt_pk_bf16_f32 v25, v30, v31
	v_cvt_pk_bf16_f32 v26, v32, v33
	v_cvt_pk_bf16_f32 v27, v34, v35
	v_pk_fma_f32 v[22:23], v[22:23], v[90:91], v[62:63] op_sel_hi:[1,0,1]
	v_pk_fma_f32 v[20:21], v[20:21], v[90:91], v[60:61] op_sel_hi:[1,0,1]
	v_pk_fma_f32 v[18:19], v[18:19], v[90:91], v[58:59] op_sel_hi:[1,0,1]
	v_max_f32_e32 v16, 0, v16
	v_max_f32_e32 v17, 0, v17
	global_store_dwordx4 v[88:89], v[24:27], off offset:256 sc1
	v_max_f32_e32 v20, 0, v20
	v_max_f32_e32 v21, 0, v21
	v_pk_mul_f32 v[24:25], v[16:17], v[16:17]
	v_max_f32_e32 v16, 0, v22
	v_max_f32_e32 v18, 0, v18
	v_max_f32_e32 v17, 0, v23
	v_max_f32_e32 v19, 0, v19
	v_pk_mul_f32 v[20:21], v[20:21], v[20:21]
	v_pk_mul_f32 v[22:23], v[16:17], v[16:17]
	v_pk_mul_f32 v[26:27], v[18:19], v[18:19]
	v_pk_fma_f32 v[8:9], v[8:9], v[146:147], v[56:57] op_sel_hi:[1,0,1]
	v_cvt_pk_bf16_f32 v16, v20, v21
	v_cvt_pk_bf16_f32 v17, v22, v23
	v_cvt_pk_bf16_f32 v18, v24, v25
	v_cvt_pk_bf16_f32 v19, v26, v27
	v_pk_fma_f32 v[14:15], v[14:15], v[146:147], v[62:63] op_sel_hi:[1,0,1]
	v_pk_fma_f32 v[12:13], v[12:13], v[146:147], v[60:61] op_sel_hi:[1,0,1]
	v_pk_fma_f32 v[10:11], v[10:11], v[146:147], v[58:59] op_sel_hi:[1,0,1]
	v_max_f32_e32 v8, 0, v8
	v_max_f32_e32 v9, 0, v9
	global_store_dwordx4 v[80:81], v[16:19], off offset:256 sc1
	v_max_f32_e32 v12, 0, v12
	v_max_f32_e32 v13, 0, v13
	v_pk_mul_f32 v[16:17], v[8:9], v[8:9]
	v_max_f32_e32 v8, 0, v14
	v_max_f32_e32 v10, 0, v10
	v_max_f32_e32 v9, 0, v15
	v_max_f32_e32 v11, 0, v11
	v_pk_mul_f32 v[12:13], v[12:13], v[12:13]
	v_pk_mul_f32 v[14:15], v[8:9], v[8:9]
	v_pk_mul_f32 v[18:19], v[10:11], v[10:11]
	v_pk_fma_f32 v[0:1], v[0:1], v[74:75], v[56:57] op_sel_hi:[1,0,1]
	v_cvt_pk_bf16_f32 v8, v12, v13
	v_cvt_pk_bf16_f32 v9, v14, v15
	v_cvt_pk_bf16_f32 v10, v16, v17
	v_cvt_pk_bf16_f32 v11, v18, v19
	v_pk_fma_f32 v[6:7], v[6:7], v[74:75], v[62:63] op_sel_hi:[1,0,1]
	v_pk_fma_f32 v[4:5], v[4:5], v[74:75], v[60:61] op_sel_hi:[1,0,1]
	v_pk_fma_f32 v[2:3], v[2:3], v[74:75], v[58:59] op_sel_hi:[1,0,1]
	v_max_f32_e32 v0, 0, v0
	v_max_f32_e32 v1, 0, v1
	global_store_dwordx4 v[72:73], v[8:11], off offset:256 sc1
	v_max_f32_e32 v4, 0, v4
	v_max_f32_e32 v5, 0, v5
	v_pk_mul_f32 v[8:9], v[0:1], v[0:1]
	v_max_f32_e32 v0, 0, v6
	v_max_f32_e32 v2, 0, v2
	v_max_f32_e32 v1, 0, v7
	v_max_f32_e32 v3, 0, v3
	v_pk_mul_f32 v[4:5], v[4:5], v[4:5]
	v_pk_mul_f32 v[6:7], v[0:1], v[0:1]
	v_pk_mul_f32 v[10:11], v[2:3], v[2:3]
	v_cvt_pk_bf16_f32 v0, v4, v5
	v_cvt_pk_bf16_f32 v1, v6, v7
	v_cvt_pk_bf16_f32 v2, v8, v9
	v_cvt_pk_bf16_f32 v3, v10, v11
	s_andn2_b64 vcc, exec, s[2:3]
	s_mov_b64 s[2:3], -1
	global_store_dwordx4 v[76:77], v[0:3], off offset:256 sc1
	s_cmp_lg_u32 s50, 0
	s_cbranch_scc1 .Lffn_pub_skip
	s_waitcnt vmcnt(0)
	s_barrier
	s_cmp_lg_u32 s67, 0
	s_cbranch_scc1 .Lffn_pub_skip
	v_readlane_b32 s22, v255, 2
	v_readlane_b32 s23, v255, 3
	s_mov_b64 s[26:27], exec
	s_mov_b64 exec, 1
	s_lshl_b32 s24, s20, 2
	v_mov_b32_e32 v4, s24
	s_nop 4
	global_atomic_add v4, v224, s[22:23]
	s_mov_b64 exec, s[26:27]
